# scan v3: chunk barrier taken at top of pair 15 + next chunk's first pair prefetched; y dots share one reduction tree (odd/even lanes)
# speedup vs baseline: 1.0081x; 1.0013x over previous
.LBB0_1092:
	s_mov_b64 s[92:93], -1
	s_and_b64 vcc, exec, s[88:89]
	s_cbranch_vccz .LBB0_1098
	s_bitcmp1_b32 s9, 0
	s_cselect_b32 s7, 0xb200, 0
	s_add_i32 s26, s7, 0
	s_xor_b32 s27, s26, 0xb200
	s_mov_b32 s20, 0xaaaaaaaa
	s_mov_b32 s21, 0xaaaaaaaa
	v_lshl_add_u32 v174, v102, 2, s26
	v_mov_b32_e32 v175, s26
	v_add_u32_e32 v163, s26, v160
	v_lshl_add_u32 v42, v102, 2, s27
	v_mov_b32_e32 v43, s27
	v_add_u32_e32 v44, s27, v160
	v_mov_b64_e32 v[144:145], v[140:141]
	v_mov_b64_e32 v[146:147], v[142:143]
	v_mov_b32_e32 v162, v111
	s_cmp_lg_u32 s9, 0
	s_cbranch_scc1 .Lscan_havep0
	ds_read_b128 v[0:3], v174 offset:0
	ds_read_b128 v[4:7], v174 offset:256
	ds_read_b128 v[8:11], v174 offset:512
	ds_read_b128 v[12:15], v174 offset:768
	ds_read_b128 v[16:19], v174 offset:1024
	ds_read_b128 v[20:23], v174 offset:1280
	ds_read_b128 v[24:27], v174 offset:1536
	ds_read_b128 v[28:31], v174 offset:1792
	ds_read_b128 v[32:35], v174 offset:2048
	ds_read_b128 v[36:39], v175 offset:2816
	ds_read_b32 v40, v163 offset:2304
	ds_read_b32 v41, v163 offset:2560
.Lscan_havep0:
	s_waitcnt lgkmcnt(0)
	v_pk_mul_f32 v[96:97], v[144:145], v[50:51]
	v_pk_mul_f32 v[98:99], v[144:145], v[0:1]
	v_pk_mul_f32 v[100:101], v[144:145], v[4:5]
	v_pk_mul_f32 v[172:173], v[144:145], v[8:9]
	v_pk_fma_f32 v[96:97], v[146:147], v[52:53], v[96:97]
	v_pk_fma_f32 v[98:99], v[146:147], v[2:3], v[98:99]
	v_pk_fma_f32 v[100:101], v[146:147], v[6:7], v[100:101]
	v_pk_fma_f32 v[172:173], v[146:147], v[10:11], v[172:173]
	ds_read_b128 v[54:57], v174 offset:2848
	ds_read_b128 v[58:61], v174 offset:3104
	ds_read_b128 v[62:65], v174 offset:3360
	ds_read_b128 v[66:69], v174 offset:3616
	ds_read_b128 v[70:73], v174 offset:3872
	ds_read_b128 v[74:77], v174 offset:4128
	ds_read_b128 v[78:81], v174 offset:4384
	ds_read_b128 v[82:85], v174 offset:4640
	ds_read_b128 v[86:89], v174 offset:4896
	ds_read_b128 v[90:93], v175 offset:5664
	ds_read_b32 v94, v163 offset:5152
	ds_read_b32 v95, v163 offset:5408
	v_pk_mul_f32 v[148:149], v[24:25], v[40:41] op_sel_hi:[1,0]
	v_pk_mul_f32 v[150:151], v[26:27], v[40:41] op_sel_hi:[1,0]
	v_add_f32_e32 v168, v96, v97
	v_add_f32_e32 v166, v98, v99
	v_add_f32_e32 v169, v100, v101
	v_add_f32_e32 v170, v172, v173
	v_pk_fma_f32 v[148:149], v[32:33], v[40:41], v[148:149] op_sel:[0,1,0] op_sel_hi:[1,1,1]
	v_pk_fma_f32 v[150:151], v[34:35], v[40:41], v[150:151] op_sel:[0,1,0] op_sel_hi:[1,1,1]
	v_add_f32_dpp v168, v168, v168 quad_perm:[1,0,3,2] row_mask:0xf bank_mask:0xf bound_ctrl:1
	v_add_f32_dpp v166, v166, v166 quad_perm:[1,0,3,2] row_mask:0xf bank_mask:0xf bound_ctrl:1
	v_add_f32_dpp v169, v169, v169 quad_perm:[1,0,3,2] row_mask:0xf bank_mask:0xf bound_ctrl:1
	v_add_f32_dpp v170, v170, v170 quad_perm:[1,0,3,2] row_mask:0xf bank_mask:0xf bound_ctrl:1
	v_cndmask_b32_e64 v168, v170, v168, s[20:21]
	v_add_f32_dpp v166, v166, v166 quad_perm:[2,3,0,1] row_mask:0xf bank_mask:0xf bound_ctrl:1
	v_add_f32_dpp v169, v169, v169 quad_perm:[2,3,0,1] row_mask:0xf bank_mask:0xf bound_ctrl:1
	v_add_f32_dpp v168, v168, v168 quad_perm:[2,3,0,1] row_mask:0xf bank_mask:0xf bound_ctrl:1
	v_add_f32_dpp v166, v166, v166 row_half_mirror row_mask:0xf bank_mask:0xf bound_ctrl:1
	v_add_f32_dpp v169, v169, v169 row_half_mirror row_mask:0xf bank_mask:0xf bound_ctrl:1
	v_add_f32_dpp v168, v168, v168 row_ror:4 row_mask:0xf bank_mask:0xf bound_ctrl:1
	v_add_f32_dpp v166, v166, v166 row_mirror row_mask:0xf bank_mask:0xf bound_ctrl:1
	v_add_f32_dpp v169, v169, v169 row_mirror row_mask:0xf bank_mask:0xf bound_ctrl:1
	v_add_f32_dpp v168, v168, v168 row_ror:8 row_mask:0xf bank_mask:0xf bound_ctrl:1
	v_fma_f32 v164, v40, v37, v169
	v_pk_fma_f32 v[148:149], v[20:21], v[166:167], v[148:149] op_sel_hi:[1,0,1]
	v_fma_f32 v171, v40, v39, v168
	v_fma_f32 v167, v166, v36, v164
	v_pk_fma_f32 v[150:151], v[22:23], v[166:167], v[150:151] op_sel_hi:[1,0,1]
	v_fma_f32 v171, v166, v38, v171
	v_cndmask_b32_e64 v162, v162, v168, s[46:47]
	s_lshl_b32 s6, s9, 1
	s_cmp_eq_u32 s6, 0
	s_cbranch_scc1 .Lscan_noy0
	s_add_i32 s6, s6, -1
	s_and_b32 s6, s6, 7
	s_lshl_b32 s6, s6, 10
	v_add_u32_e32 v161, s6, v156
	ds_write_b32 v161, v162
.Lscan_noy0:
	v_pk_fma_f32 v[148:149], v[28:29], v[166:167], v[148:149] op_sel:[0,1,0] op_sel_hi:[1,1,1]
	v_pk_fma_f32 v[150:151], v[30:31], v[166:167], v[150:151] op_sel:[0,1,0] op_sel_hi:[1,1,1]
	v_cndmask_b32_e64 v162, v162, v171, s[38:39]
	v_pk_fma_f32 v[144:145], v[144:145], v[16:17], v[148:149]
	v_pk_fma_f32 v[146:147], v[146:147], v[18:19], v[150:151]
	s_waitcnt lgkmcnt(0)
	v_pk_mul_f32 v[96:97], v[144:145], v[12:13]
	v_pk_mul_f32 v[98:99], v[144:145], v[54:55]
	v_pk_mul_f32 v[100:101], v[144:145], v[58:59]
	v_pk_mul_f32 v[172:173], v[144:145], v[62:63]
	v_pk_fma_f32 v[96:97], v[146:147], v[14:15], v[96:97]
	v_pk_fma_f32 v[98:99], v[146:147], v[56:57], v[98:99]
	v_pk_fma_f32 v[100:101], v[146:147], v[60:61], v[100:101]
	v_pk_fma_f32 v[172:173], v[146:147], v[64:65], v[172:173]
	ds_read_b128 v[0:3], v174 offset:5696
	ds_read_b128 v[4:7], v174 offset:5952
	ds_read_b128 v[8:11], v174 offset:6208
	ds_read_b128 v[12:15], v174 offset:6464
	ds_read_b128 v[16:19], v174 offset:6720
	ds_read_b128 v[20:23], v174 offset:6976
	ds_read_b128 v[24:27], v174 offset:7232
	ds_read_b128 v[28:31], v174 offset:7488
	ds_read_b128 v[32:35], v174 offset:7744
	ds_read_b128 v[36:39], v175 offset:8512
	ds_read_b32 v40, v163 offset:8000
	ds_read_b32 v41, v163 offset:8256
	v_pk_mul_f32 v[148:149], v[78:79], v[94:95] op_sel_hi:[1,0]
	v_pk_mul_f32 v[150:151], v[80:81], v[94:95] op_sel_hi:[1,0]
	v_add_f32_e32 v168, v96, v97
	v_add_f32_e32 v166, v98, v99
	v_add_f32_e32 v169, v100, v101
	v_add_f32_e32 v170, v172, v173
	v_pk_fma_f32 v[148:149], v[86:87], v[94:95], v[148:149] op_sel:[0,1,0] op_sel_hi:[1,1,1]
	v_pk_fma_f32 v[150:151], v[88:89], v[94:95], v[150:151] op_sel:[0,1,0] op_sel_hi:[1,1,1]
	v_add_f32_dpp v168, v168, v168 quad_perm:[1,0,3,2] row_mask:0xf bank_mask:0xf bound_ctrl:1
	v_add_f32_dpp v166, v166, v166 quad_perm:[1,0,3,2] row_mask:0xf bank_mask:0xf bound_ctrl:1
	v_add_f32_dpp v169, v169, v169 quad_perm:[1,0,3,2] row_mask:0xf bank_mask:0xf bound_ctrl:1
	v_add_f32_dpp v170, v170, v170 quad_perm:[1,0,3,2] row_mask:0xf bank_mask:0xf bound_ctrl:1
	v_cndmask_b32_e64 v168, v170, v168, s[20:21]
	v_add_f32_dpp v166, v166, v166 quad_perm:[2,3,0,1] row_mask:0xf bank_mask:0xf bound_ctrl:1
	v_add_f32_dpp v169, v169, v169 quad_perm:[2,3,0,1] row_mask:0xf bank_mask:0xf bound_ctrl:1
	v_add_f32_dpp v168, v168, v168 quad_perm:[2,3,0,1] row_mask:0xf bank_mask:0xf bound_ctrl:1
	v_add_f32_dpp v166, v166, v166 row_half_mirror row_mask:0xf bank_mask:0xf bound_ctrl:1
	v_add_f32_dpp v169, v169, v169 row_half_mirror row_mask:0xf bank_mask:0xf bound_ctrl:1
	v_add_f32_dpp v168, v168, v168 row_ror:4 row_mask:0xf bank_mask:0xf bound_ctrl:1
	v_add_f32_dpp v166, v166, v166 row_mirror row_mask:0xf bank_mask:0xf bound_ctrl:1
	v_add_f32_dpp v169, v169, v169 row_mirror row_mask:0xf bank_mask:0xf bound_ctrl:1
	v_add_f32_dpp v168, v168, v168 row_ror:8 row_mask:0xf bank_mask:0xf bound_ctrl:1
	v_fma_f32 v164, v94, v91, v169
	v_pk_fma_f32 v[148:149], v[74:75], v[166:167], v[148:149] op_sel_hi:[1,0,1]
	v_fma_f32 v171, v94, v93, v168
	v_fma_f32 v167, v166, v90, v164
	v_pk_fma_f32 v[150:151], v[76:77], v[166:167], v[150:151] op_sel_hi:[1,0,1]
	v_fma_f32 v171, v166, v92, v171
	v_cndmask_b32_e64 v162, v162, v168, s[48:49]
	v_pk_fma_f32 v[148:149], v[82:83], v[166:167], v[148:149] op_sel:[0,1,0] op_sel_hi:[1,1,1]
	v_pk_fma_f32 v[150:151], v[84:85], v[166:167], v[150:151] op_sel:[0,1,0] op_sel_hi:[1,1,1]
	v_cndmask_b32_e64 v162, v162, v171, s[50:51]
	v_pk_fma_f32 v[144:145], v[144:145], v[70:71], v[148:149]
	v_pk_fma_f32 v[146:147], v[146:147], v[72:73], v[150:151]
	s_waitcnt lgkmcnt(0)
	v_pk_mul_f32 v[96:97], v[144:145], v[66:67]
	v_pk_mul_f32 v[98:99], v[144:145], v[0:1]
	v_pk_mul_f32 v[100:101], v[144:145], v[4:5]
	v_pk_mul_f32 v[172:173], v[144:145], v[8:9]
	v_pk_fma_f32 v[96:97], v[146:147], v[68:69], v[96:97]
	v_pk_fma_f32 v[98:99], v[146:147], v[2:3], v[98:99]
	v_pk_fma_f32 v[100:101], v[146:147], v[6:7], v[100:101]
	v_pk_fma_f32 v[172:173], v[146:147], v[10:11], v[172:173]
	ds_read_b128 v[54:57], v174 offset:8544
	ds_read_b128 v[58:61], v174 offset:8800
	ds_read_b128 v[62:65], v174 offset:9056
	ds_read_b128 v[66:69], v174 offset:9312
	ds_read_b128 v[70:73], v174 offset:9568
	ds_read_b128 v[74:77], v174 offset:9824
	ds_read_b128 v[78:81], v174 offset:10080
	ds_read_b128 v[82:85], v174 offset:10336
	ds_read_b128 v[86:89], v174 offset:10592
	ds_read_b128 v[90:93], v175 offset:11360
	ds_read_b32 v94, v163 offset:10848
	ds_read_b32 v95, v163 offset:11104
	v_pk_mul_f32 v[148:149], v[24:25], v[40:41] op_sel_hi:[1,0]
	v_pk_mul_f32 v[150:151], v[26:27], v[40:41] op_sel_hi:[1,0]
	v_add_f32_e32 v168, v96, v97
	v_add_f32_e32 v166, v98, v99
	v_add_f32_e32 v169, v100, v101
	v_add_f32_e32 v170, v172, v173
	v_pk_fma_f32 v[148:149], v[32:33], v[40:41], v[148:149] op_sel:[0,1,0] op_sel_hi:[1,1,1]
	v_pk_fma_f32 v[150:151], v[34:35], v[40:41], v[150:151] op_sel:[0,1,0] op_sel_hi:[1,1,1]
	v_add_f32_dpp v168, v168, v168 quad_perm:[1,0,3,2] row_mask:0xf bank_mask:0xf bound_ctrl:1
	v_add_f32_dpp v166, v166, v166 quad_perm:[1,0,3,2] row_mask:0xf bank_mask:0xf bound_ctrl:1
	v_add_f32_dpp v169, v169, v169 quad_perm:[1,0,3,2] row_mask:0xf bank_mask:0xf bound_ctrl:1
	v_add_f32_dpp v170, v170, v170 quad_perm:[1,0,3,2] row_mask:0xf bank_mask:0xf bound_ctrl:1
	v_cndmask_b32_e64 v168, v170, v168, s[20:21]
	v_add_f32_dpp v166, v166, v166 quad_perm:[2,3,0,1] row_mask:0xf bank_mask:0xf bound_ctrl:1
	v_add_f32_dpp v169, v169, v169 quad_perm:[2,3,0,1] row_mask:0xf bank_mask:0xf bound_ctrl:1
	v_add_f32_dpp v168, v168, v168 quad_perm:[2,3,0,1] row_mask:0xf bank_mask:0xf bound_ctrl:1
	v_add_f32_dpp v166, v166, v166 row_half_mirror row_mask:0xf bank_mask:0xf bound_ctrl:1
	v_add_f32_dpp v169, v169, v169 row_half_mirror row_mask:0xf bank_mask:0xf bound_ctrl:1
	v_add_f32_dpp v168, v168, v168 row_ror:4 row_mask:0xf bank_mask:0xf bound_ctrl:1
	v_add_f32_dpp v166, v166, v166 row_mirror row_mask:0xf bank_mask:0xf bound_ctrl:1
	v_add_f32_dpp v169, v169, v169 row_mirror row_mask:0xf bank_mask:0xf bound_ctrl:1
	v_add_f32_dpp v168, v168, v168 row_ror:8 row_mask:0xf bank_mask:0xf bound_ctrl:1
	v_fma_f32 v164, v40, v37, v169
	v_pk_fma_f32 v[148:149], v[20:21], v[166:167], v[148:149] op_sel_hi:[1,0,1]
	v_fma_f32 v171, v40, v39, v168
	v_fma_f32 v167, v166, v36, v164
	v_pk_fma_f32 v[150:151], v[22:23], v[166:167], v[150:151] op_sel_hi:[1,0,1]
	v_fma_f32 v171, v166, v38, v171
	v_cndmask_b32_e64 v162, v162, v168, s[52:53]
	v_pk_fma_f32 v[148:149], v[28:29], v[166:167], v[148:149] op_sel:[0,1,0] op_sel_hi:[1,1,1]
	v_pk_fma_f32 v[150:151], v[30:31], v[166:167], v[150:151] op_sel:[0,1,0] op_sel_hi:[1,1,1]
	v_cndmask_b32_e64 v162, v162, v171, s[54:55]
	v_pk_fma_f32 v[144:145], v[144:145], v[16:17], v[148:149]
	v_pk_fma_f32 v[146:147], v[146:147], v[18:19], v[150:151]
	s_waitcnt lgkmcnt(0)
	v_pk_mul_f32 v[96:97], v[144:145], v[12:13]
	v_pk_mul_f32 v[98:99], v[144:145], v[54:55]
	v_pk_mul_f32 v[100:101], v[144:145], v[58:59]
	v_pk_mul_f32 v[172:173], v[144:145], v[62:63]
	v_pk_fma_f32 v[96:97], v[146:147], v[14:15], v[96:97]
	v_pk_fma_f32 v[98:99], v[146:147], v[56:57], v[98:99]
	v_pk_fma_f32 v[100:101], v[146:147], v[60:61], v[100:101]
	v_pk_fma_f32 v[172:173], v[146:147], v[64:65], v[172:173]
	ds_read_b128 v[0:3], v174 offset:11392
	ds_read_b128 v[4:7], v174 offset:11648
	ds_read_b128 v[8:11], v174 offset:11904
	ds_read_b128 v[12:15], v174 offset:12160
	ds_read_b128 v[16:19], v174 offset:12416
	ds_read_b128 v[20:23], v174 offset:12672
	ds_read_b128 v[24:27], v174 offset:12928
	ds_read_b128 v[28:31], v174 offset:13184
	ds_read_b128 v[32:35], v174 offset:13440
	ds_read_b128 v[36:39], v175 offset:14208
	ds_read_b32 v40, v163 offset:13696
	ds_read_b32 v41, v163 offset:13952
	v_pk_mul_f32 v[148:149], v[78:79], v[94:95] op_sel_hi:[1,0]
	v_pk_mul_f32 v[150:151], v[80:81], v[94:95] op_sel_hi:[1,0]
	v_add_f32_e32 v168, v96, v97
	v_add_f32_e32 v166, v98, v99
	v_add_f32_e32 v169, v100, v101
	v_add_f32_e32 v170, v172, v173
	v_pk_fma_f32 v[148:149], v[86:87], v[94:95], v[148:149] op_sel:[0,1,0] op_sel_hi:[1,1,1]
	v_pk_fma_f32 v[150:151], v[88:89], v[94:95], v[150:151] op_sel:[0,1,0] op_sel_hi:[1,1,1]
	v_add_f32_dpp v168, v168, v168 quad_perm:[1,0,3,2] row_mask:0xf bank_mask:0xf bound_ctrl:1
	v_add_f32_dpp v166, v166, v166 quad_perm:[1,0,3,2] row_mask:0xf bank_mask:0xf bound_ctrl:1
	v_add_f32_dpp v169, v169, v169 quad_perm:[1,0,3,2] row_mask:0xf bank_mask:0xf bound_ctrl:1
	v_add_f32_dpp v170, v170, v170 quad_perm:[1,0,3,2] row_mask:0xf bank_mask:0xf bound_ctrl:1
	v_cndmask_b32_e64 v168, v170, v168, s[20:21]
	v_add_f32_dpp v166, v166, v166 quad_perm:[2,3,0,1] row_mask:0xf bank_mask:0xf bound_ctrl:1
	v_add_f32_dpp v169, v169, v169 quad_perm:[2,3,0,1] row_mask:0xf bank_mask:0xf bound_ctrl:1
	v_add_f32_dpp v168, v168, v168 quad_perm:[2,3,0,1] row_mask:0xf bank_mask:0xf bound_ctrl:1
	v_add_f32_dpp v166, v166, v166 row_half_mirror row_mask:0xf bank_mask:0xf bound_ctrl:1
	v_add_f32_dpp v169, v169, v169 row_half_mirror row_mask:0xf bank_mask:0xf bound_ctrl:1
	v_add_f32_dpp v168, v168, v168 row_ror:4 row_mask:0xf bank_mask:0xf bound_ctrl:1
	v_add_f32_dpp v166, v166, v166 row_mirror row_mask:0xf bank_mask:0xf bound_ctrl:1
	v_add_f32_dpp v169, v169, v169 row_mirror row_mask:0xf bank_mask:0xf bound_ctrl:1
	v_add_f32_dpp v168, v168, v168 row_ror:8 row_mask:0xf bank_mask:0xf bound_ctrl:1
	v_fma_f32 v164, v94, v91, v169
	v_pk_fma_f32 v[148:149], v[74:75], v[166:167], v[148:149] op_sel_hi:[1,0,1]
	v_fma_f32 v171, v94, v93, v168
	v_fma_f32 v167, v166, v90, v164
	v_pk_fma_f32 v[150:151], v[76:77], v[166:167], v[150:151] op_sel_hi:[1,0,1]
	v_fma_f32 v171, v166, v92, v171
	v_cndmask_b32_e64 v162, v162, v168, s[56:57]
	v_pk_fma_f32 v[148:149], v[82:83], v[166:167], v[148:149] op_sel:[0,1,0] op_sel_hi:[1,1,1]
	v_pk_fma_f32 v[150:151], v[84:85], v[166:167], v[150:151] op_sel:[0,1,0] op_sel_hi:[1,1,1]
	v_cndmask_b32_e64 v162, v162, v171, s[58:59]
	v_pk_fma_f32 v[144:145], v[144:145], v[70:71], v[148:149]
	v_pk_fma_f32 v[146:147], v[146:147], v[72:73], v[150:151]
	s_waitcnt lgkmcnt(0)
	v_pk_mul_f32 v[96:97], v[144:145], v[66:67]
	v_pk_mul_f32 v[98:99], v[144:145], v[0:1]
	v_pk_mul_f32 v[100:101], v[144:145], v[4:5]
	v_pk_mul_f32 v[172:173], v[144:145], v[8:9]
	v_pk_fma_f32 v[96:97], v[146:147], v[68:69], v[96:97]
	v_pk_fma_f32 v[98:99], v[146:147], v[2:3], v[98:99]
	v_pk_fma_f32 v[100:101], v[146:147], v[6:7], v[100:101]
	v_pk_fma_f32 v[172:173], v[146:147], v[10:11], v[172:173]
	ds_read_b128 v[54:57], v174 offset:14240
	ds_read_b128 v[58:61], v174 offset:14496
	ds_read_b128 v[62:65], v174 offset:14752
	ds_read_b128 v[66:69], v174 offset:15008
	ds_read_b128 v[70:73], v174 offset:15264
	ds_read_b128 v[74:77], v174 offset:15520
	ds_read_b128 v[78:81], v174 offset:15776
	ds_read_b128 v[82:85], v174 offset:16032
	ds_read_b128 v[86:89], v174 offset:16288
	ds_read_b128 v[90:93], v175 offset:17056
	ds_read_b32 v94, v163 offset:16544
	ds_read_b32 v95, v163 offset:16800
	v_pk_mul_f32 v[148:149], v[24:25], v[40:41] op_sel_hi:[1,0]
	v_pk_mul_f32 v[150:151], v[26:27], v[40:41] op_sel_hi:[1,0]
	v_add_f32_e32 v168, v96, v97
	v_add_f32_e32 v166, v98, v99
	v_add_f32_e32 v169, v100, v101
	v_add_f32_e32 v170, v172, v173
	v_pk_fma_f32 v[148:149], v[32:33], v[40:41], v[148:149] op_sel:[0,1,0] op_sel_hi:[1,1,1]
	v_pk_fma_f32 v[150:151], v[34:35], v[40:41], v[150:151] op_sel:[0,1,0] op_sel_hi:[1,1,1]
	v_add_f32_dpp v168, v168, v168 quad_perm:[1,0,3,2] row_mask:0xf bank_mask:0xf bound_ctrl:1
	v_add_f32_dpp v166, v166, v166 quad_perm:[1,0,3,2] row_mask:0xf bank_mask:0xf bound_ctrl:1
	v_add_f32_dpp v169, v169, v169 quad_perm:[1,0,3,2] row_mask:0xf bank_mask:0xf bound_ctrl:1
	v_add_f32_dpp v170, v170, v170 quad_perm:[1,0,3,2] row_mask:0xf bank_mask:0xf bound_ctrl:1
	v_cndmask_b32_e64 v168, v170, v168, s[20:21]
	v_add_f32_dpp v166, v166, v166 quad_perm:[2,3,0,1] row_mask:0xf bank_mask:0xf bound_ctrl:1
	v_add_f32_dpp v169, v169, v169 quad_perm:[2,3,0,1] row_mask:0xf bank_mask:0xf bound_ctrl:1
	v_add_f32_dpp v168, v168, v168 quad_perm:[2,3,0,1] row_mask:0xf bank_mask:0xf bound_ctrl:1
	v_add_f32_dpp v166, v166, v166 row_half_mirror row_mask:0xf bank_mask:0xf bound_ctrl:1
	v_add_f32_dpp v169, v169, v169 row_half_mirror row_mask:0xf bank_mask:0xf bound_ctrl:1
	v_add_f32_dpp v168, v168, v168 row_ror:4 row_mask:0xf bank_mask:0xf bound_ctrl:1
	v_add_f32_dpp v166, v166, v166 row_mirror row_mask:0xf bank_mask:0xf bound_ctrl:1
	v_add_f32_dpp v169, v169, v169 row_mirror row_mask:0xf bank_mask:0xf bound_ctrl:1
	v_add_f32_dpp v168, v168, v168 row_ror:8 row_mask:0xf bank_mask:0xf bound_ctrl:1
	v_fma_f32 v164, v40, v37, v169
	v_pk_fma_f32 v[148:149], v[20:21], v[166:167], v[148:149] op_sel_hi:[1,0,1]
	v_fma_f32 v171, v40, v39, v168
	v_fma_f32 v167, v166, v36, v164
	v_pk_fma_f32 v[150:151], v[22:23], v[166:167], v[150:151] op_sel_hi:[1,0,1]
	v_fma_f32 v171, v166, v38, v171
	v_cndmask_b32_e64 v162, v162, v168, s[60:61]
	v_pk_fma_f32 v[148:149], v[28:29], v[166:167], v[148:149] op_sel:[0,1,0] op_sel_hi:[1,1,1]
	v_pk_fma_f32 v[150:151], v[30:31], v[166:167], v[150:151] op_sel:[0,1,0] op_sel_hi:[1,1,1]
	v_cndmask_b32_e64 v162, v162, v171, s[62:63]
	v_pk_fma_f32 v[144:145], v[144:145], v[16:17], v[148:149]
	v_pk_fma_f32 v[146:147], v[146:147], v[18:19], v[150:151]
	s_waitcnt lgkmcnt(0)
	v_pk_mul_f32 v[96:97], v[144:145], v[12:13]
	v_pk_mul_f32 v[98:99], v[144:145], v[54:55]
	v_pk_mul_f32 v[100:101], v[144:145], v[58:59]
	v_pk_mul_f32 v[172:173], v[144:145], v[62:63]
	v_pk_fma_f32 v[96:97], v[146:147], v[14:15], v[96:97]
	v_pk_fma_f32 v[98:99], v[146:147], v[56:57], v[98:99]
	v_pk_fma_f32 v[100:101], v[146:147], v[60:61], v[100:101]
	v_pk_fma_f32 v[172:173], v[146:147], v[64:65], v[172:173]
	ds_read_b128 v[0:3], v174 offset:17088
	ds_read_b128 v[4:7], v174 offset:17344
	ds_read_b128 v[8:11], v174 offset:17600
	ds_read_b128 v[12:15], v174 offset:17856
	ds_read_b128 v[16:19], v174 offset:18112
	ds_read_b128 v[20:23], v174 offset:18368
	ds_read_b128 v[24:27], v174 offset:18624
	ds_read_b128 v[28:31], v174 offset:18880
	ds_read_b128 v[32:35], v174 offset:19136
	ds_read_b128 v[36:39], v175 offset:19904
	ds_read_b32 v40, v163 offset:19392
	ds_read_b32 v41, v163 offset:19648
	v_pk_mul_f32 v[148:149], v[78:79], v[94:95] op_sel_hi:[1,0]
	v_pk_mul_f32 v[150:151], v[80:81], v[94:95] op_sel_hi:[1,0]
	v_add_f32_e32 v168, v96, v97
	v_add_f32_e32 v166, v98, v99
	v_add_f32_e32 v169, v100, v101
	v_add_f32_e32 v170, v172, v173
	v_pk_fma_f32 v[148:149], v[86:87], v[94:95], v[148:149] op_sel:[0,1,0] op_sel_hi:[1,1,1]
	v_pk_fma_f32 v[150:151], v[88:89], v[94:95], v[150:151] op_sel:[0,1,0] op_sel_hi:[1,1,1]
	v_add_f32_dpp v168, v168, v168 quad_perm:[1,0,3,2] row_mask:0xf bank_mask:0xf bound_ctrl:1
	v_add_f32_dpp v166, v166, v166 quad_perm:[1,0,3,2] row_mask:0xf bank_mask:0xf bound_ctrl:1
	v_add_f32_dpp v169, v169, v169 quad_perm:[1,0,3,2] row_mask:0xf bank_mask:0xf bound_ctrl:1
	v_add_f32_dpp v170, v170, v170 quad_perm:[1,0,3,2] row_mask:0xf bank_mask:0xf bound_ctrl:1
	v_cndmask_b32_e64 v168, v170, v168, s[20:21]
	v_add_f32_dpp v166, v166, v166 quad_perm:[2,3,0,1] row_mask:0xf bank_mask:0xf bound_ctrl:1
	v_add_f32_dpp v169, v169, v169 quad_perm:[2,3,0,1] row_mask:0xf bank_mask:0xf bound_ctrl:1
	v_add_f32_dpp v168, v168, v168 quad_perm:[2,3,0,1] row_mask:0xf bank_mask:0xf bound_ctrl:1
	v_add_f32_dpp v166, v166, v166 row_half_mirror row_mask:0xf bank_mask:0xf bound_ctrl:1
	v_add_f32_dpp v169, v169, v169 row_half_mirror row_mask:0xf bank_mask:0xf bound_ctrl:1
	v_add_f32_dpp v168, v168, v168 row_ror:4 row_mask:0xf bank_mask:0xf bound_ctrl:1
	v_add_f32_dpp v166, v166, v166 row_mirror row_mask:0xf bank_mask:0xf bound_ctrl:1
	v_add_f32_dpp v169, v169, v169 row_mirror row_mask:0xf bank_mask:0xf bound_ctrl:1
	v_add_f32_dpp v168, v168, v168 row_ror:8 row_mask:0xf bank_mask:0xf bound_ctrl:1
	v_fma_f32 v164, v94, v91, v169
	v_pk_fma_f32 v[148:149], v[74:75], v[166:167], v[148:149] op_sel_hi:[1,0,1]
	v_fma_f32 v171, v94, v93, v168
	v_fma_f32 v167, v166, v90, v164
	v_pk_fma_f32 v[150:151], v[76:77], v[166:167], v[150:151] op_sel_hi:[1,0,1]
	v_fma_f32 v171, v166, v92, v171
	v_cndmask_b32_e64 v162, v162, v168, s[64:65]
	v_pk_fma_f32 v[148:149], v[82:83], v[166:167], v[148:149] op_sel:[0,1,0] op_sel_hi:[1,1,1]
	v_pk_fma_f32 v[150:151], v[84:85], v[166:167], v[150:151] op_sel:[0,1,0] op_sel_hi:[1,1,1]
	v_cndmask_b32_e64 v162, v162, v171, s[66:67]
	v_pk_fma_f32 v[144:145], v[144:145], v[70:71], v[148:149]
	v_pk_fma_f32 v[146:147], v[146:147], v[72:73], v[150:151]
	s_waitcnt lgkmcnt(0)
	v_pk_mul_f32 v[96:97], v[144:145], v[66:67]
	v_pk_mul_f32 v[98:99], v[144:145], v[0:1]
	v_pk_mul_f32 v[100:101], v[144:145], v[4:5]
	v_pk_mul_f32 v[172:173], v[144:145], v[8:9]
	v_pk_fma_f32 v[96:97], v[146:147], v[68:69], v[96:97]
	v_pk_fma_f32 v[98:99], v[146:147], v[2:3], v[98:99]
	v_pk_fma_f32 v[100:101], v[146:147], v[6:7], v[100:101]
	v_pk_fma_f32 v[172:173], v[146:147], v[10:11], v[172:173]
	ds_read_b128 v[54:57], v174 offset:19936
	ds_read_b128 v[58:61], v174 offset:20192
	ds_read_b128 v[62:65], v174 offset:20448
	ds_read_b128 v[66:69], v174 offset:20704
	ds_read_b128 v[70:73], v174 offset:20960
	ds_read_b128 v[74:77], v174 offset:21216
	ds_read_b128 v[78:81], v174 offset:21472
	ds_read_b128 v[82:85], v174 offset:21728
	ds_read_b128 v[86:89], v174 offset:21984
	ds_read_b128 v[90:93], v175 offset:22752
	ds_read_b32 v94, v163 offset:22240
	ds_read_b32 v95, v163 offset:22496
	v_pk_mul_f32 v[148:149], v[24:25], v[40:41] op_sel_hi:[1,0]
	v_pk_mul_f32 v[150:151], v[26:27], v[40:41] op_sel_hi:[1,0]
	v_add_f32_e32 v168, v96, v97
	v_add_f32_e32 v166, v98, v99
	v_add_f32_e32 v169, v100, v101
	v_add_f32_e32 v170, v172, v173
	v_pk_fma_f32 v[148:149], v[32:33], v[40:41], v[148:149] op_sel:[0,1,0] op_sel_hi:[1,1,1]
	v_pk_fma_f32 v[150:151], v[34:35], v[40:41], v[150:151] op_sel:[0,1,0] op_sel_hi:[1,1,1]
	v_add_f32_dpp v168, v168, v168 quad_perm:[1,0,3,2] row_mask:0xf bank_mask:0xf bound_ctrl:1
	v_add_f32_dpp v166, v166, v166 quad_perm:[1,0,3,2] row_mask:0xf bank_mask:0xf bound_ctrl:1
	v_add_f32_dpp v169, v169, v169 quad_perm:[1,0,3,2] row_mask:0xf bank_mask:0xf bound_ctrl:1
	v_add_f32_dpp v170, v170, v170 quad_perm:[1,0,3,2] row_mask:0xf bank_mask:0xf bound_ctrl:1
	v_cndmask_b32_e64 v168, v170, v168, s[20:21]
	v_add_f32_dpp v166, v166, v166 quad_perm:[2,3,0,1] row_mask:0xf bank_mask:0xf bound_ctrl:1
	v_add_f32_dpp v169, v169, v169 quad_perm:[2,3,0,1] row_mask:0xf bank_mask:0xf bound_ctrl:1
	v_add_f32_dpp v168, v168, v168 quad_perm:[2,3,0,1] row_mask:0xf bank_mask:0xf bound_ctrl:1
	v_add_f32_dpp v166, v166, v166 row_half_mirror row_mask:0xf bank_mask:0xf bound_ctrl:1
	v_add_f32_dpp v169, v169, v169 row_half_mirror row_mask:0xf bank_mask:0xf bound_ctrl:1
	v_add_f32_dpp v168, v168, v168 row_ror:4 row_mask:0xf bank_mask:0xf bound_ctrl:1
	v_add_f32_dpp v166, v166, v166 row_mirror row_mask:0xf bank_mask:0xf bound_ctrl:1
	v_add_f32_dpp v169, v169, v169 row_mirror row_mask:0xf bank_mask:0xf bound_ctrl:1
	v_add_f32_dpp v168, v168, v168 row_ror:8 row_mask:0xf bank_mask:0xf bound_ctrl:1
	v_fma_f32 v164, v40, v37, v169
	v_pk_fma_f32 v[148:149], v[20:21], v[166:167], v[148:149] op_sel_hi:[1,0,1]
	v_fma_f32 v171, v40, v39, v168
	v_fma_f32 v167, v166, v36, v164
	v_pk_fma_f32 v[150:151], v[22:23], v[166:167], v[150:151] op_sel_hi:[1,0,1]
	v_fma_f32 v171, v166, v38, v171
	v_cndmask_b32_e64 v162, v162, v168, s[68:69]
	v_pk_fma_f32 v[148:149], v[28:29], v[166:167], v[148:149] op_sel:[0,1,0] op_sel_hi:[1,1,1]
	v_pk_fma_f32 v[150:151], v[30:31], v[166:167], v[150:151] op_sel:[0,1,0] op_sel_hi:[1,1,1]
	v_cndmask_b32_e64 v162, v162, v171, s[70:71]
	v_pk_fma_f32 v[144:145], v[144:145], v[16:17], v[148:149]
	v_pk_fma_f32 v[146:147], v[146:147], v[18:19], v[150:151]
	s_waitcnt lgkmcnt(0)
	v_pk_mul_f32 v[96:97], v[144:145], v[12:13]
	v_pk_mul_f32 v[98:99], v[144:145], v[54:55]
	v_pk_mul_f32 v[100:101], v[144:145], v[58:59]
	v_pk_mul_f32 v[172:173], v[144:145], v[62:63]
	v_pk_fma_f32 v[96:97], v[146:147], v[14:15], v[96:97]
	v_pk_fma_f32 v[98:99], v[146:147], v[56:57], v[98:99]
	v_pk_fma_f32 v[100:101], v[146:147], v[60:61], v[100:101]
	v_pk_fma_f32 v[172:173], v[146:147], v[64:65], v[172:173]
	ds_read_b128 v[0:3], v174 offset:22784
	ds_read_b128 v[4:7], v174 offset:23040
	ds_read_b128 v[8:11], v174 offset:23296
	ds_read_b128 v[12:15], v174 offset:23552
	ds_read_b128 v[16:19], v174 offset:23808
	ds_read_b128 v[20:23], v174 offset:24064
	ds_read_b128 v[24:27], v174 offset:24320
	ds_read_b128 v[28:31], v174 offset:24576
	ds_read_b128 v[32:35], v174 offset:24832
	ds_read_b128 v[36:39], v175 offset:25600
	ds_read_b32 v40, v163 offset:25088
	ds_read_b32 v41, v163 offset:25344
	v_pk_mul_f32 v[148:149], v[78:79], v[94:95] op_sel_hi:[1,0]
	v_pk_mul_f32 v[150:151], v[80:81], v[94:95] op_sel_hi:[1,0]
	v_add_f32_e32 v168, v96, v97
	v_add_f32_e32 v166, v98, v99
	v_add_f32_e32 v169, v100, v101
	v_add_f32_e32 v170, v172, v173
	v_pk_fma_f32 v[148:149], v[86:87], v[94:95], v[148:149] op_sel:[0,1,0] op_sel_hi:[1,1,1]
	v_pk_fma_f32 v[150:151], v[88:89], v[94:95], v[150:151] op_sel:[0,1,0] op_sel_hi:[1,1,1]
	v_add_f32_dpp v168, v168, v168 quad_perm:[1,0,3,2] row_mask:0xf bank_mask:0xf bound_ctrl:1
	v_add_f32_dpp v166, v166, v166 quad_perm:[1,0,3,2] row_mask:0xf bank_mask:0xf bound_ctrl:1
	v_add_f32_dpp v169, v169, v169 quad_perm:[1,0,3,2] row_mask:0xf bank_mask:0xf bound_ctrl:1
	v_add_f32_dpp v170, v170, v170 quad_perm:[1,0,3,2] row_mask:0xf bank_mask:0xf bound_ctrl:1
	v_cndmask_b32_e64 v168, v170, v168, s[20:21]
	v_add_f32_dpp v166, v166, v166 quad_perm:[2,3,0,1] row_mask:0xf bank_mask:0xf bound_ctrl:1
	v_add_f32_dpp v169, v169, v169 quad_perm:[2,3,0,1] row_mask:0xf bank_mask:0xf bound_ctrl:1
	v_add_f32_dpp v168, v168, v168 quad_perm:[2,3,0,1] row_mask:0xf bank_mask:0xf bound_ctrl:1
	v_add_f32_dpp v166, v166, v166 row_half_mirror row_mask:0xf bank_mask:0xf bound_ctrl:1
	v_add_f32_dpp v169, v169, v169 row_half_mirror row_mask:0xf bank_mask:0xf bound_ctrl:1
	v_add_f32_dpp v168, v168, v168 row_ror:4 row_mask:0xf bank_mask:0xf bound_ctrl:1
	v_add_f32_dpp v166, v166, v166 row_mirror row_mask:0xf bank_mask:0xf bound_ctrl:1
	v_add_f32_dpp v169, v169, v169 row_mirror row_mask:0xf bank_mask:0xf bound_ctrl:1
	v_add_f32_dpp v168, v168, v168 row_ror:8 row_mask:0xf bank_mask:0xf bound_ctrl:1
	v_fma_f32 v164, v94, v91, v169
	v_pk_fma_f32 v[148:149], v[74:75], v[166:167], v[148:149] op_sel_hi:[1,0,1]
	v_fma_f32 v171, v94, v93, v168
	v_fma_f32 v167, v166, v90, v164
	v_pk_fma_f32 v[150:151], v[76:77], v[166:167], v[150:151] op_sel_hi:[1,0,1]
	v_fma_f32 v171, v166, v92, v171
	v_cndmask_b32_e64 v162, v162, v168, s[44:45]
	v_pk_fma_f32 v[148:149], v[82:83], v[166:167], v[148:149] op_sel:[0,1,0] op_sel_hi:[1,1,1]
	v_pk_fma_f32 v[150:151], v[84:85], v[166:167], v[150:151] op_sel:[0,1,0] op_sel_hi:[1,1,1]
	v_cndmask_b32_e64 v162, v162, v171, s[42:43]
	v_pk_fma_f32 v[144:145], v[144:145], v[70:71], v[148:149]
	v_pk_fma_f32 v[146:147], v[146:147], v[72:73], v[150:151]
	s_waitcnt lgkmcnt(0)
	v_pk_mul_f32 v[96:97], v[144:145], v[66:67]
	v_pk_mul_f32 v[98:99], v[144:145], v[0:1]
	v_pk_mul_f32 v[100:101], v[144:145], v[4:5]
	v_pk_mul_f32 v[172:173], v[144:145], v[8:9]
	v_pk_fma_f32 v[96:97], v[146:147], v[68:69], v[96:97]
	v_pk_fma_f32 v[98:99], v[146:147], v[2:3], v[98:99]
	v_pk_fma_f32 v[100:101], v[146:147], v[6:7], v[100:101]
	v_pk_fma_f32 v[172:173], v[146:147], v[10:11], v[172:173]
	ds_read_b128 v[54:57], v174 offset:25632
	ds_read_b128 v[58:61], v174 offset:25888
	ds_read_b128 v[62:65], v174 offset:26144
	ds_read_b128 v[66:69], v174 offset:26400
	ds_read_b128 v[70:73], v174 offset:26656
	ds_read_b128 v[74:77], v174 offset:26912
	ds_read_b128 v[78:81], v174 offset:27168
	ds_read_b128 v[82:85], v174 offset:27424
	ds_read_b128 v[86:89], v174 offset:27680
	ds_read_b128 v[90:93], v175 offset:28448
	ds_read_b32 v94, v163 offset:27936
	ds_read_b32 v95, v163 offset:28192
	v_pk_mul_f32 v[148:149], v[24:25], v[40:41] op_sel_hi:[1,0]
	v_pk_mul_f32 v[150:151], v[26:27], v[40:41] op_sel_hi:[1,0]
	v_add_f32_e32 v168, v96, v97
	v_add_f32_e32 v166, v98, v99
	v_add_f32_e32 v169, v100, v101
	v_add_f32_e32 v170, v172, v173
	v_pk_fma_f32 v[148:149], v[32:33], v[40:41], v[148:149] op_sel:[0,1,0] op_sel_hi:[1,1,1]
	v_pk_fma_f32 v[150:151], v[34:35], v[40:41], v[150:151] op_sel:[0,1,0] op_sel_hi:[1,1,1]
	v_add_f32_dpp v168, v168, v168 quad_perm:[1,0,3,2] row_mask:0xf bank_mask:0xf bound_ctrl:1
	v_add_f32_dpp v166, v166, v166 quad_perm:[1,0,3,2] row_mask:0xf bank_mask:0xf bound_ctrl:1
	v_add_f32_dpp v169, v169, v169 quad_perm:[1,0,3,2] row_mask:0xf bank_mask:0xf bound_ctrl:1
	v_add_f32_dpp v170, v170, v170 quad_perm:[1,0,3,2] row_mask:0xf bank_mask:0xf bound_ctrl:1
	v_cndmask_b32_e64 v168, v170, v168, s[20:21]
	v_add_f32_dpp v166, v166, v166 quad_perm:[2,3,0,1] row_mask:0xf bank_mask:0xf bound_ctrl:1
	v_add_f32_dpp v169, v169, v169 quad_perm:[2,3,0,1] row_mask:0xf bank_mask:0xf bound_ctrl:1
	v_add_f32_dpp v168, v168, v168 quad_perm:[2,3,0,1] row_mask:0xf bank_mask:0xf bound_ctrl:1
	v_add_f32_dpp v166, v166, v166 row_half_mirror row_mask:0xf bank_mask:0xf bound_ctrl:1
	v_add_f32_dpp v169, v169, v169 row_half_mirror row_mask:0xf bank_mask:0xf bound_ctrl:1
	v_add_f32_dpp v168, v168, v168 row_ror:4 row_mask:0xf bank_mask:0xf bound_ctrl:1
	v_add_f32_dpp v166, v166, v166 row_mirror row_mask:0xf bank_mask:0xf bound_ctrl:1
	v_add_f32_dpp v169, v169, v169 row_mirror row_mask:0xf bank_mask:0xf bound_ctrl:1
	v_add_f32_dpp v168, v168, v168 row_ror:8 row_mask:0xf bank_mask:0xf bound_ctrl:1
	v_fma_f32 v164, v40, v37, v169
	v_pk_fma_f32 v[148:149], v[20:21], v[166:167], v[148:149] op_sel_hi:[1,0,1]
	v_fma_f32 v171, v40, v39, v168
	v_fma_f32 v167, v166, v36, v164
	v_pk_fma_f32 v[150:151], v[22:23], v[166:167], v[150:151] op_sel_hi:[1,0,1]
	v_fma_f32 v171, v166, v38, v171
	v_cndmask_b32_e64 v162, v162, v168, s[46:47]
	s_lshl_b32 s6, s9, 1
	s_add_i32 s6, s6, 1
	s_add_i32 s6, s6, -1
	s_and_b32 s6, s6, 7
	s_lshl_b32 s6, s6, 10
	v_add_u32_e32 v161, s6, v156
	ds_write_b32 v161, v162
	v_pk_fma_f32 v[148:149], v[28:29], v[166:167], v[148:149] op_sel:[0,1,0] op_sel_hi:[1,1,1]
	v_pk_fma_f32 v[150:151], v[30:31], v[166:167], v[150:151] op_sel:[0,1,0] op_sel_hi:[1,1,1]
	v_cndmask_b32_e64 v162, v162, v171, s[38:39]
	v_pk_fma_f32 v[144:145], v[144:145], v[16:17], v[148:149]
	v_pk_fma_f32 v[146:147], v[146:147], v[18:19], v[150:151]
	s_waitcnt lgkmcnt(0)
	v_pk_mul_f32 v[96:97], v[144:145], v[12:13]
	v_pk_mul_f32 v[98:99], v[144:145], v[54:55]
	v_pk_mul_f32 v[100:101], v[144:145], v[58:59]
	v_pk_mul_f32 v[172:173], v[144:145], v[62:63]
	v_pk_fma_f32 v[96:97], v[146:147], v[14:15], v[96:97]
	v_pk_fma_f32 v[98:99], v[146:147], v[56:57], v[98:99]
	v_pk_fma_f32 v[100:101], v[146:147], v[60:61], v[100:101]
	v_pk_fma_f32 v[172:173], v[146:147], v[64:65], v[172:173]
	ds_read_b128 v[0:3], v174 offset:28480
	ds_read_b128 v[4:7], v174 offset:28736
	ds_read_b128 v[8:11], v174 offset:28992
	ds_read_b128 v[12:15], v174 offset:29248
	ds_read_b128 v[16:19], v174 offset:29504
	ds_read_b128 v[20:23], v174 offset:29760
	ds_read_b128 v[24:27], v174 offset:30016
	ds_read_b128 v[28:31], v174 offset:30272
	ds_read_b128 v[32:35], v174 offset:30528
	ds_read_b128 v[36:39], v175 offset:31296
	ds_read_b32 v40, v163 offset:30784
	ds_read_b32 v41, v163 offset:31040
	v_pk_mul_f32 v[148:149], v[78:79], v[94:95] op_sel_hi:[1,0]
	v_pk_mul_f32 v[150:151], v[80:81], v[94:95] op_sel_hi:[1,0]
	v_add_f32_e32 v168, v96, v97
	v_add_f32_e32 v166, v98, v99
	v_add_f32_e32 v169, v100, v101
	v_add_f32_e32 v170, v172, v173
	v_pk_fma_f32 v[148:149], v[86:87], v[94:95], v[148:149] op_sel:[0,1,0] op_sel_hi:[1,1,1]
	v_pk_fma_f32 v[150:151], v[88:89], v[94:95], v[150:151] op_sel:[0,1,0] op_sel_hi:[1,1,1]
	v_add_f32_dpp v168, v168, v168 quad_perm:[1,0,3,2] row_mask:0xf bank_mask:0xf bound_ctrl:1
	v_add_f32_dpp v166, v166, v166 quad_perm:[1,0,3,2] row_mask:0xf bank_mask:0xf bound_ctrl:1
	v_add_f32_dpp v169, v169, v169 quad_perm:[1,0,3,2] row_mask:0xf bank_mask:0xf bound_ctrl:1
	v_add_f32_dpp v170, v170, v170 quad_perm:[1,0,3,2] row_mask:0xf bank_mask:0xf bound_ctrl:1
	v_cndmask_b32_e64 v168, v170, v168, s[20:21]
	v_add_f32_dpp v166, v166, v166 quad_perm:[2,3,0,1] row_mask:0xf bank_mask:0xf bound_ctrl:1
	v_add_f32_dpp v169, v169, v169 quad_perm:[2,3,0,1] row_mask:0xf bank_mask:0xf bound_ctrl:1
	v_add_f32_dpp v168, v168, v168 quad_perm:[2,3,0,1] row_mask:0xf bank_mask:0xf bound_ctrl:1
	v_add_f32_dpp v166, v166, v166 row_half_mirror row_mask:0xf bank_mask:0xf bound_ctrl:1
	v_add_f32_dpp v169, v169, v169 row_half_mirror row_mask:0xf bank_mask:0xf bound_ctrl:1
	v_add_f32_dpp v168, v168, v168 row_ror:4 row_mask:0xf bank_mask:0xf bound_ctrl:1
	v_add_f32_dpp v166, v166, v166 row_mirror row_mask:0xf bank_mask:0xf bound_ctrl:1
	v_add_f32_dpp v169, v169, v169 row_mirror row_mask:0xf bank_mask:0xf bound_ctrl:1
	v_add_f32_dpp v168, v168, v168 row_ror:8 row_mask:0xf bank_mask:0xf bound_ctrl:1
	v_fma_f32 v164, v94, v91, v169
	v_pk_fma_f32 v[148:149], v[74:75], v[166:167], v[148:149] op_sel_hi:[1,0,1]
	v_fma_f32 v171, v94, v93, v168
	v_fma_f32 v167, v166, v90, v164
	v_pk_fma_f32 v[150:151], v[76:77], v[166:167], v[150:151] op_sel_hi:[1,0,1]
	v_fma_f32 v171, v166, v92, v171
	v_cndmask_b32_e64 v162, v162, v168, s[48:49]
	v_pk_fma_f32 v[148:149], v[82:83], v[166:167], v[148:149] op_sel:[0,1,0] op_sel_hi:[1,1,1]
	v_pk_fma_f32 v[150:151], v[84:85], v[166:167], v[150:151] op_sel:[0,1,0] op_sel_hi:[1,1,1]
	v_cndmask_b32_e64 v162, v162, v171, s[50:51]
	v_pk_fma_f32 v[144:145], v[144:145], v[70:71], v[148:149]
	v_pk_fma_f32 v[146:147], v[146:147], v[72:73], v[150:151]
	s_waitcnt lgkmcnt(0)
	v_pk_mul_f32 v[96:97], v[144:145], v[66:67]
	v_pk_mul_f32 v[98:99], v[144:145], v[0:1]
	v_pk_mul_f32 v[100:101], v[144:145], v[4:5]
	v_pk_mul_f32 v[172:173], v[144:145], v[8:9]
	v_pk_fma_f32 v[96:97], v[146:147], v[68:69], v[96:97]
	v_pk_fma_f32 v[98:99], v[146:147], v[2:3], v[98:99]
	v_pk_fma_f32 v[100:101], v[146:147], v[6:7], v[100:101]
	v_pk_fma_f32 v[172:173], v[146:147], v[10:11], v[172:173]
	ds_read_b128 v[54:57], v174 offset:31328
	ds_read_b128 v[58:61], v174 offset:31584
	ds_read_b128 v[62:65], v174 offset:31840
	ds_read_b128 v[66:69], v174 offset:32096
	ds_read_b128 v[70:73], v174 offset:32352
	ds_read_b128 v[74:77], v174 offset:32608
	ds_read_b128 v[78:81], v174 offset:32864
	ds_read_b128 v[82:85], v174 offset:33120
	ds_read_b128 v[86:89], v174 offset:33376
	ds_read_b128 v[90:93], v175 offset:34144
	ds_read_b32 v94, v163 offset:33632
	ds_read_b32 v95, v163 offset:33888
	v_pk_mul_f32 v[148:149], v[24:25], v[40:41] op_sel_hi:[1,0]
	v_pk_mul_f32 v[150:151], v[26:27], v[40:41] op_sel_hi:[1,0]
	v_add_f32_e32 v168, v96, v97
	v_add_f32_e32 v166, v98, v99
	v_add_f32_e32 v169, v100, v101
	v_add_f32_e32 v170, v172, v173
	v_pk_fma_f32 v[148:149], v[32:33], v[40:41], v[148:149] op_sel:[0,1,0] op_sel_hi:[1,1,1]
	v_pk_fma_f32 v[150:151], v[34:35], v[40:41], v[150:151] op_sel:[0,1,0] op_sel_hi:[1,1,1]
	v_add_f32_dpp v168, v168, v168 quad_perm:[1,0,3,2] row_mask:0xf bank_mask:0xf bound_ctrl:1
	v_add_f32_dpp v166, v166, v166 quad_perm:[1,0,3,2] row_mask:0xf bank_mask:0xf bound_ctrl:1
	v_add_f32_dpp v169, v169, v169 quad_perm:[1,0,3,2] row_mask:0xf bank_mask:0xf bound_ctrl:1
	v_add_f32_dpp v170, v170, v170 quad_perm:[1,0,3,2] row_mask:0xf bank_mask:0xf bound_ctrl:1
	v_cndmask_b32_e64 v168, v170, v168, s[20:21]
	v_add_f32_dpp v166, v166, v166 quad_perm:[2,3,0,1] row_mask:0xf bank_mask:0xf bound_ctrl:1
	v_add_f32_dpp v169, v169, v169 quad_perm:[2,3,0,1] row_mask:0xf bank_mask:0xf bound_ctrl:1
	v_add_f32_dpp v168, v168, v168 quad_perm:[2,3,0,1] row_mask:0xf bank_mask:0xf bound_ctrl:1
	v_add_f32_dpp v166, v166, v166 row_half_mirror row_mask:0xf bank_mask:0xf bound_ctrl:1
	v_add_f32_dpp v169, v169, v169 row_half_mirror row_mask:0xf bank_mask:0xf bound_ctrl:1
	v_add_f32_dpp v168, v168, v168 row_ror:4 row_mask:0xf bank_mask:0xf bound_ctrl:1
	v_add_f32_dpp v166, v166, v166 row_mirror row_mask:0xf bank_mask:0xf bound_ctrl:1
	v_add_f32_dpp v169, v169, v169 row_mirror row_mask:0xf bank_mask:0xf bound_ctrl:1
	v_add_f32_dpp v168, v168, v168 row_ror:8 row_mask:0xf bank_mask:0xf bound_ctrl:1
	v_fma_f32 v164, v40, v37, v169
	v_pk_fma_f32 v[148:149], v[20:21], v[166:167], v[148:149] op_sel_hi:[1,0,1]
	v_fma_f32 v171, v40, v39, v168
	v_fma_f32 v167, v166, v36, v164
	v_pk_fma_f32 v[150:151], v[22:23], v[166:167], v[150:151] op_sel_hi:[1,0,1]
	v_fma_f32 v171, v166, v38, v171
	v_cndmask_b32_e64 v162, v162, v168, s[52:53]
	v_pk_fma_f32 v[148:149], v[28:29], v[166:167], v[148:149] op_sel:[0,1,0] op_sel_hi:[1,1,1]
	v_pk_fma_f32 v[150:151], v[30:31], v[166:167], v[150:151] op_sel:[0,1,0] op_sel_hi:[1,1,1]
	v_cndmask_b32_e64 v162, v162, v171, s[54:55]
	v_pk_fma_f32 v[144:145], v[144:145], v[16:17], v[148:149]
	v_pk_fma_f32 v[146:147], v[146:147], v[18:19], v[150:151]
	s_waitcnt lgkmcnt(0)
	v_pk_mul_f32 v[96:97], v[144:145], v[12:13]
	v_pk_mul_f32 v[98:99], v[144:145], v[54:55]
	v_pk_mul_f32 v[100:101], v[144:145], v[58:59]
	v_pk_mul_f32 v[172:173], v[144:145], v[62:63]
	v_pk_fma_f32 v[96:97], v[146:147], v[14:15], v[96:97]
	v_pk_fma_f32 v[98:99], v[146:147], v[56:57], v[98:99]
	v_pk_fma_f32 v[100:101], v[146:147], v[60:61], v[100:101]
	v_pk_fma_f32 v[172:173], v[146:147], v[64:65], v[172:173]
	ds_read_b128 v[0:3], v174 offset:34176
	ds_read_b128 v[4:7], v174 offset:34432
	ds_read_b128 v[8:11], v174 offset:34688
	ds_read_b128 v[12:15], v174 offset:34944
	ds_read_b128 v[16:19], v174 offset:35200
	ds_read_b128 v[20:23], v174 offset:35456
	ds_read_b128 v[24:27], v174 offset:35712
	ds_read_b128 v[28:31], v174 offset:35968
	ds_read_b128 v[32:35], v174 offset:36224
	ds_read_b128 v[36:39], v175 offset:36992
	ds_read_b32 v40, v163 offset:36480
	ds_read_b32 v41, v163 offset:36736
	v_pk_mul_f32 v[148:149], v[78:79], v[94:95] op_sel_hi:[1,0]
	v_pk_mul_f32 v[150:151], v[80:81], v[94:95] op_sel_hi:[1,0]
	v_add_f32_e32 v168, v96, v97
	v_add_f32_e32 v166, v98, v99
	v_add_f32_e32 v169, v100, v101
	v_add_f32_e32 v170, v172, v173
	v_pk_fma_f32 v[148:149], v[86:87], v[94:95], v[148:149] op_sel:[0,1,0] op_sel_hi:[1,1,1]
	v_pk_fma_f32 v[150:151], v[88:89], v[94:95], v[150:151] op_sel:[0,1,0] op_sel_hi:[1,1,1]
	v_add_f32_dpp v168, v168, v168 quad_perm:[1,0,3,2] row_mask:0xf bank_mask:0xf bound_ctrl:1
	v_add_f32_dpp v166, v166, v166 quad_perm:[1,0,3,2] row_mask:0xf bank_mask:0xf bound_ctrl:1
	v_add_f32_dpp v169, v169, v169 quad_perm:[1,0,3,2] row_mask:0xf bank_mask:0xf bound_ctrl:1
	v_add_f32_dpp v170, v170, v170 quad_perm:[1,0,3,2] row_mask:0xf bank_mask:0xf bound_ctrl:1
	v_cndmask_b32_e64 v168, v170, v168, s[20:21]
	v_add_f32_dpp v166, v166, v166 quad_perm:[2,3,0,1] row_mask:0xf bank_mask:0xf bound_ctrl:1
	v_add_f32_dpp v169, v169, v169 quad_perm:[2,3,0,1] row_mask:0xf bank_mask:0xf bound_ctrl:1
	v_add_f32_dpp v168, v168, v168 quad_perm:[2,3,0,1] row_mask:0xf bank_mask:0xf bound_ctrl:1
	v_add_f32_dpp v166, v166, v166 row_half_mirror row_mask:0xf bank_mask:0xf bound_ctrl:1
	v_add_f32_dpp v169, v169, v169 row_half_mirror row_mask:0xf bank_mask:0xf bound_ctrl:1
	v_add_f32_dpp v168, v168, v168 row_ror:4 row_mask:0xf bank_mask:0xf bound_ctrl:1
	v_add_f32_dpp v166, v166, v166 row_mirror row_mask:0xf bank_mask:0xf bound_ctrl:1
	v_add_f32_dpp v169, v169, v169 row_mirror row_mask:0xf bank_mask:0xf bound_ctrl:1
	v_add_f32_dpp v168, v168, v168 row_ror:8 row_mask:0xf bank_mask:0xf bound_ctrl:1
	v_fma_f32 v164, v94, v91, v169
	v_pk_fma_f32 v[148:149], v[74:75], v[166:167], v[148:149] op_sel_hi:[1,0,1]
	v_fma_f32 v171, v94, v93, v168
	v_fma_f32 v167, v166, v90, v164
	v_pk_fma_f32 v[150:151], v[76:77], v[166:167], v[150:151] op_sel_hi:[1,0,1]
	v_fma_f32 v171, v166, v92, v171
	v_cndmask_b32_e64 v162, v162, v168, s[56:57]
	v_pk_fma_f32 v[148:149], v[82:83], v[166:167], v[148:149] op_sel:[0,1,0] op_sel_hi:[1,1,1]
	v_pk_fma_f32 v[150:151], v[84:85], v[166:167], v[150:151] op_sel:[0,1,0] op_sel_hi:[1,1,1]
	v_cndmask_b32_e64 v162, v162, v171, s[58:59]
	v_pk_fma_f32 v[144:145], v[144:145], v[70:71], v[148:149]
	v_pk_fma_f32 v[146:147], v[146:147], v[72:73], v[150:151]
	s_waitcnt lgkmcnt(0)
	v_pk_mul_f32 v[96:97], v[144:145], v[66:67]
	v_pk_mul_f32 v[98:99], v[144:145], v[0:1]
	v_pk_mul_f32 v[100:101], v[144:145], v[4:5]
	v_pk_mul_f32 v[172:173], v[144:145], v[8:9]
	v_pk_fma_f32 v[96:97], v[146:147], v[68:69], v[96:97]
	v_pk_fma_f32 v[98:99], v[146:147], v[2:3], v[98:99]
	v_pk_fma_f32 v[100:101], v[146:147], v[6:7], v[100:101]
	v_pk_fma_f32 v[172:173], v[146:147], v[10:11], v[172:173]
	ds_read_b128 v[54:57], v174 offset:37024
	ds_read_b128 v[58:61], v174 offset:37280
	ds_read_b128 v[62:65], v174 offset:37536
	ds_read_b128 v[66:69], v174 offset:37792
	ds_read_b128 v[70:73], v174 offset:38048
	ds_read_b128 v[74:77], v174 offset:38304
	ds_read_b128 v[78:81], v174 offset:38560
	ds_read_b128 v[82:85], v174 offset:38816
	ds_read_b128 v[86:89], v174 offset:39072
	ds_read_b128 v[90:93], v175 offset:39840
	ds_read_b32 v94, v163 offset:39328
	ds_read_b32 v95, v163 offset:39584
	v_pk_mul_f32 v[148:149], v[24:25], v[40:41] op_sel_hi:[1,0]
	v_pk_mul_f32 v[150:151], v[26:27], v[40:41] op_sel_hi:[1,0]
	v_add_f32_e32 v168, v96, v97
	v_add_f32_e32 v166, v98, v99
	v_add_f32_e32 v169, v100, v101
	v_add_f32_e32 v170, v172, v173
	v_pk_fma_f32 v[148:149], v[32:33], v[40:41], v[148:149] op_sel:[0,1,0] op_sel_hi:[1,1,1]
	v_pk_fma_f32 v[150:151], v[34:35], v[40:41], v[150:151] op_sel:[0,1,0] op_sel_hi:[1,1,1]
	v_add_f32_dpp v168, v168, v168 quad_perm:[1,0,3,2] row_mask:0xf bank_mask:0xf bound_ctrl:1
	v_add_f32_dpp v166, v166, v166 quad_perm:[1,0,3,2] row_mask:0xf bank_mask:0xf bound_ctrl:1
	v_add_f32_dpp v169, v169, v169 quad_perm:[1,0,3,2] row_mask:0xf bank_mask:0xf bound_ctrl:1
	v_add_f32_dpp v170, v170, v170 quad_perm:[1,0,3,2] row_mask:0xf bank_mask:0xf bound_ctrl:1
	v_cndmask_b32_e64 v168, v170, v168, s[20:21]
	v_add_f32_dpp v166, v166, v166 quad_perm:[2,3,0,1] row_mask:0xf bank_mask:0xf bound_ctrl:1
	v_add_f32_dpp v169, v169, v169 quad_perm:[2,3,0,1] row_mask:0xf bank_mask:0xf bound_ctrl:1
	v_add_f32_dpp v168, v168, v168 quad_perm:[2,3,0,1] row_mask:0xf bank_mask:0xf bound_ctrl:1
	v_add_f32_dpp v166, v166, v166 row_half_mirror row_mask:0xf bank_mask:0xf bound_ctrl:1
	v_add_f32_dpp v169, v169, v169 row_half_mirror row_mask:0xf bank_mask:0xf bound_ctrl:1
	v_add_f32_dpp v168, v168, v168 row_ror:4 row_mask:0xf bank_mask:0xf bound_ctrl:1
	v_add_f32_dpp v166, v166, v166 row_mirror row_mask:0xf bank_mask:0xf bound_ctrl:1
	v_add_f32_dpp v169, v169, v169 row_mirror row_mask:0xf bank_mask:0xf bound_ctrl:1
	v_add_f32_dpp v168, v168, v168 row_ror:8 row_mask:0xf bank_mask:0xf bound_ctrl:1
	v_fma_f32 v164, v40, v37, v169
	v_pk_fma_f32 v[148:149], v[20:21], v[166:167], v[148:149] op_sel_hi:[1,0,1]
	v_fma_f32 v171, v40, v39, v168
	v_fma_f32 v167, v166, v36, v164
	v_pk_fma_f32 v[150:151], v[22:23], v[166:167], v[150:151] op_sel_hi:[1,0,1]
	v_fma_f32 v171, v166, v38, v171
	v_cndmask_b32_e64 v162, v162, v168, s[60:61]
	v_pk_fma_f32 v[148:149], v[28:29], v[166:167], v[148:149] op_sel:[0,1,0] op_sel_hi:[1,1,1]
	v_pk_fma_f32 v[150:151], v[30:31], v[166:167], v[150:151] op_sel:[0,1,0] op_sel_hi:[1,1,1]
	v_cndmask_b32_e64 v162, v162, v171, s[62:63]
	v_pk_fma_f32 v[144:145], v[144:145], v[16:17], v[148:149]
	v_pk_fma_f32 v[146:147], v[146:147], v[18:19], v[150:151]
	s_waitcnt lgkmcnt(0)
	v_pk_mul_f32 v[96:97], v[144:145], v[12:13]
	v_pk_mul_f32 v[98:99], v[144:145], v[54:55]
	v_pk_mul_f32 v[100:101], v[144:145], v[58:59]
	v_pk_mul_f32 v[172:173], v[144:145], v[62:63]
	v_pk_fma_f32 v[96:97], v[146:147], v[14:15], v[96:97]
	v_pk_fma_f32 v[98:99], v[146:147], v[56:57], v[98:99]
	v_pk_fma_f32 v[100:101], v[146:147], v[60:61], v[100:101]
	v_pk_fma_f32 v[172:173], v[146:147], v[64:65], v[172:173]
	ds_read_b128 v[0:3], v174 offset:39872
	ds_read_b128 v[4:7], v174 offset:40128
	ds_read_b128 v[8:11], v174 offset:40384
	ds_read_b128 v[12:15], v174 offset:40640
	ds_read_b128 v[16:19], v174 offset:40896
	ds_read_b128 v[20:23], v174 offset:41152
	ds_read_b128 v[24:27], v174 offset:41408
	ds_read_b128 v[28:31], v174 offset:41664
	ds_read_b128 v[32:35], v174 offset:41920
	ds_read_b128 v[36:39], v175 offset:42688
	ds_read_b32 v40, v163 offset:42176
	ds_read_b32 v41, v163 offset:42432
	v_pk_mul_f32 v[148:149], v[78:79], v[94:95] op_sel_hi:[1,0]
	v_pk_mul_f32 v[150:151], v[80:81], v[94:95] op_sel_hi:[1,0]
	v_add_f32_e32 v168, v96, v97
	v_add_f32_e32 v166, v98, v99
	v_add_f32_e32 v169, v100, v101
	v_add_f32_e32 v170, v172, v173
	v_pk_fma_f32 v[148:149], v[86:87], v[94:95], v[148:149] op_sel:[0,1,0] op_sel_hi:[1,1,1]
	v_pk_fma_f32 v[150:151], v[88:89], v[94:95], v[150:151] op_sel:[0,1,0] op_sel_hi:[1,1,1]
	v_add_f32_dpp v168, v168, v168 quad_perm:[1,0,3,2] row_mask:0xf bank_mask:0xf bound_ctrl:1
	v_add_f32_dpp v166, v166, v166 quad_perm:[1,0,3,2] row_mask:0xf bank_mask:0xf bound_ctrl:1
	v_add_f32_dpp v169, v169, v169 quad_perm:[1,0,3,2] row_mask:0xf bank_mask:0xf bound_ctrl:1
	v_add_f32_dpp v170, v170, v170 quad_perm:[1,0,3,2] row_mask:0xf bank_mask:0xf bound_ctrl:1
	v_cndmask_b32_e64 v168, v170, v168, s[20:21]
	v_add_f32_dpp v166, v166, v166 quad_perm:[2,3,0,1] row_mask:0xf bank_mask:0xf bound_ctrl:1
	v_add_f32_dpp v169, v169, v169 quad_perm:[2,3,0,1] row_mask:0xf bank_mask:0xf bound_ctrl:1
	v_add_f32_dpp v168, v168, v168 quad_perm:[2,3,0,1] row_mask:0xf bank_mask:0xf bound_ctrl:1
	v_add_f32_dpp v166, v166, v166 row_half_mirror row_mask:0xf bank_mask:0xf bound_ctrl:1
	v_add_f32_dpp v169, v169, v169 row_half_mirror row_mask:0xf bank_mask:0xf bound_ctrl:1
	v_add_f32_dpp v168, v168, v168 row_ror:4 row_mask:0xf bank_mask:0xf bound_ctrl:1
	v_add_f32_dpp v166, v166, v166 row_mirror row_mask:0xf bank_mask:0xf bound_ctrl:1
	v_add_f32_dpp v169, v169, v169 row_mirror row_mask:0xf bank_mask:0xf bound_ctrl:1
	v_add_f32_dpp v168, v168, v168 row_ror:8 row_mask:0xf bank_mask:0xf bound_ctrl:1
	v_fma_f32 v164, v94, v91, v169
	v_pk_fma_f32 v[148:149], v[74:75], v[166:167], v[148:149] op_sel_hi:[1,0,1]
	v_fma_f32 v171, v94, v93, v168
	v_fma_f32 v167, v166, v90, v164
	v_pk_fma_f32 v[150:151], v[76:77], v[166:167], v[150:151] op_sel_hi:[1,0,1]
	v_fma_f32 v171, v166, v92, v171
	v_cndmask_b32_e64 v162, v162, v168, s[64:65]
	v_pk_fma_f32 v[148:149], v[82:83], v[166:167], v[148:149] op_sel:[0,1,0] op_sel_hi:[1,1,1]
	v_pk_fma_f32 v[150:151], v[84:85], v[166:167], v[150:151] op_sel:[0,1,0] op_sel_hi:[1,1,1]
	v_cndmask_b32_e64 v162, v162, v171, s[66:67]
	v_pk_fma_f32 v[144:145], v[144:145], v[70:71], v[148:149]
	v_pk_fma_f32 v[146:147], v[146:147], v[72:73], v[150:151]
	s_waitcnt lgkmcnt(0)
	v_pk_mul_f32 v[96:97], v[144:145], v[66:67]
	v_pk_mul_f32 v[98:99], v[144:145], v[0:1]
	v_pk_mul_f32 v[100:101], v[144:145], v[4:5]
	v_pk_mul_f32 v[172:173], v[144:145], v[8:9]
	v_pk_fma_f32 v[96:97], v[146:147], v[68:69], v[96:97]
	v_pk_fma_f32 v[98:99], v[146:147], v[2:3], v[98:99]
	v_pk_fma_f32 v[100:101], v[146:147], v[6:7], v[100:101]
	v_pk_fma_f32 v[172:173], v[146:147], v[10:11], v[172:173]
	ds_read_b128 v[54:57], v174 offset:42720
	ds_read_b128 v[58:61], v174 offset:42976
	ds_read_b128 v[62:65], v174 offset:43232
	ds_read_b128 v[66:69], v174 offset:43488
	ds_read_b128 v[70:73], v174 offset:43744
	ds_read_b128 v[74:77], v174 offset:44000
	ds_read_b128 v[78:81], v174 offset:44256
	ds_read_b128 v[82:85], v174 offset:44512
	ds_read_b128 v[86:89], v174 offset:44768
	ds_read_b128 v[90:93], v175 offset:45536
	ds_read_b32 v94, v163 offset:45024
	ds_read_b32 v95, v163 offset:45280
	v_pk_mul_f32 v[148:149], v[24:25], v[40:41] op_sel_hi:[1,0]
	v_pk_mul_f32 v[150:151], v[26:27], v[40:41] op_sel_hi:[1,0]
	v_add_f32_e32 v168, v96, v97
	v_add_f32_e32 v166, v98, v99
	v_add_f32_e32 v169, v100, v101
	v_add_f32_e32 v170, v172, v173
	v_pk_fma_f32 v[148:149], v[32:33], v[40:41], v[148:149] op_sel:[0,1,0] op_sel_hi:[1,1,1]
	v_pk_fma_f32 v[150:151], v[34:35], v[40:41], v[150:151] op_sel:[0,1,0] op_sel_hi:[1,1,1]
	v_add_f32_dpp v168, v168, v168 quad_perm:[1,0,3,2] row_mask:0xf bank_mask:0xf bound_ctrl:1
	v_add_f32_dpp v166, v166, v166 quad_perm:[1,0,3,2] row_mask:0xf bank_mask:0xf bound_ctrl:1
	v_add_f32_dpp v169, v169, v169 quad_perm:[1,0,3,2] row_mask:0xf bank_mask:0xf bound_ctrl:1
	v_add_f32_dpp v170, v170, v170 quad_perm:[1,0,3,2] row_mask:0xf bank_mask:0xf bound_ctrl:1
	v_cndmask_b32_e64 v168, v170, v168, s[20:21]
	v_add_f32_dpp v166, v166, v166 quad_perm:[2,3,0,1] row_mask:0xf bank_mask:0xf bound_ctrl:1
	v_add_f32_dpp v169, v169, v169 quad_perm:[2,3,0,1] row_mask:0xf bank_mask:0xf bound_ctrl:1
	v_add_f32_dpp v168, v168, v168 quad_perm:[2,3,0,1] row_mask:0xf bank_mask:0xf bound_ctrl:1
	v_add_f32_dpp v166, v166, v166 row_half_mirror row_mask:0xf bank_mask:0xf bound_ctrl:1
	v_add_f32_dpp v169, v169, v169 row_half_mirror row_mask:0xf bank_mask:0xf bound_ctrl:1
	v_add_f32_dpp v168, v168, v168 row_ror:4 row_mask:0xf bank_mask:0xf bound_ctrl:1
	v_add_f32_dpp v166, v166, v166 row_mirror row_mask:0xf bank_mask:0xf bound_ctrl:1
	v_add_f32_dpp v169, v169, v169 row_mirror row_mask:0xf bank_mask:0xf bound_ctrl:1
	v_add_f32_dpp v168, v168, v168 row_ror:8 row_mask:0xf bank_mask:0xf bound_ctrl:1
	v_fma_f32 v164, v40, v37, v169
	v_pk_fma_f32 v[148:149], v[20:21], v[166:167], v[148:149] op_sel_hi:[1,0,1]
	v_fma_f32 v171, v40, v39, v168
	v_fma_f32 v167, v166, v36, v164
	v_pk_fma_f32 v[150:151], v[22:23], v[166:167], v[150:151] op_sel_hi:[1,0,1]
	v_fma_f32 v171, v166, v38, v171
	v_cndmask_b32_e64 v162, v162, v168, s[68:69]
	v_pk_fma_f32 v[148:149], v[28:29], v[166:167], v[148:149] op_sel:[0,1,0] op_sel_hi:[1,1,1]
	v_pk_fma_f32 v[150:151], v[30:31], v[166:167], v[150:151] op_sel:[0,1,0] op_sel_hi:[1,1,1]
	v_cndmask_b32_e64 v162, v162, v171, s[70:71]
	v_pk_fma_f32 v[144:145], v[144:145], v[16:17], v[148:149]
	v_pk_fma_f32 v[146:147], v[146:147], v[18:19], v[150:151]
	s_waitcnt lgkmcnt(0)
	v_pk_mul_f32 v[96:97], v[144:145], v[12:13]
	v_pk_mul_f32 v[98:99], v[144:145], v[54:55]
	v_pk_mul_f32 v[100:101], v[144:145], v[58:59]
	v_pk_mul_f32 v[172:173], v[144:145], v[62:63]
	v_pk_fma_f32 v[96:97], v[146:147], v[14:15], v[96:97]
	v_pk_fma_f32 v[98:99], v[146:147], v[56:57], v[98:99]
	v_pk_fma_f32 v[100:101], v[146:147], v[60:61], v[100:101]
	v_pk_fma_f32 v[172:173], v[146:147], v[64:65], v[172:173]
	s_barrier
	s_cmp_eq_u32 s9, 63
	s_cbranch_scc1 .Lscan_nonext
	ds_read_b128 v[0:3], v42 offset:0
	ds_read_b128 v[4:7], v42 offset:256
	ds_read_b128 v[8:11], v42 offset:512
	ds_read_b128 v[12:15], v42 offset:768
	ds_read_b128 v[16:19], v42 offset:1024
	ds_read_b128 v[20:23], v42 offset:1280
	ds_read_b128 v[24:27], v42 offset:1536
	ds_read_b128 v[28:31], v42 offset:1792
	ds_read_b128 v[32:35], v42 offset:2048
	ds_read_b128 v[36:39], v43 offset:2816
	ds_read_b32 v40, v44 offset:2304
	ds_read_b32 v41, v44 offset:2560
.Lscan_nonext:
	v_pk_mul_f32 v[148:149], v[78:79], v[94:95] op_sel_hi:[1,0]
	v_pk_mul_f32 v[150:151], v[80:81], v[94:95] op_sel_hi:[1,0]
	v_add_f32_e32 v168, v96, v97
	v_add_f32_e32 v166, v98, v99
	v_add_f32_e32 v169, v100, v101
	v_add_f32_e32 v170, v172, v173
	v_pk_fma_f32 v[148:149], v[86:87], v[94:95], v[148:149] op_sel:[0,1,0] op_sel_hi:[1,1,1]
	v_pk_fma_f32 v[150:151], v[88:89], v[94:95], v[150:151] op_sel:[0,1,0] op_sel_hi:[1,1,1]
	v_add_f32_dpp v168, v168, v168 quad_perm:[1,0,3,2] row_mask:0xf bank_mask:0xf bound_ctrl:1
	v_add_f32_dpp v166, v166, v166 quad_perm:[1,0,3,2] row_mask:0xf bank_mask:0xf bound_ctrl:1
	v_add_f32_dpp v169, v169, v169 quad_perm:[1,0,3,2] row_mask:0xf bank_mask:0xf bound_ctrl:1
	v_add_f32_dpp v170, v170, v170 quad_perm:[1,0,3,2] row_mask:0xf bank_mask:0xf bound_ctrl:1
	v_cndmask_b32_e64 v168, v170, v168, s[20:21]
	v_add_f32_dpp v166, v166, v166 quad_perm:[2,3,0,1] row_mask:0xf bank_mask:0xf bound_ctrl:1
	v_add_f32_dpp v169, v169, v169 quad_perm:[2,3,0,1] row_mask:0xf bank_mask:0xf bound_ctrl:1
	v_add_f32_dpp v168, v168, v168 quad_perm:[2,3,0,1] row_mask:0xf bank_mask:0xf bound_ctrl:1
	v_add_f32_dpp v166, v166, v166 row_half_mirror row_mask:0xf bank_mask:0xf bound_ctrl:1
	v_add_f32_dpp v169, v169, v169 row_half_mirror row_mask:0xf bank_mask:0xf bound_ctrl:1
	v_add_f32_dpp v168, v168, v168 row_ror:4 row_mask:0xf bank_mask:0xf bound_ctrl:1
	v_add_f32_dpp v166, v166, v166 row_mirror row_mask:0xf bank_mask:0xf bound_ctrl:1
	v_add_f32_dpp v169, v169, v169 row_mirror row_mask:0xf bank_mask:0xf bound_ctrl:1
	v_add_f32_dpp v168, v168, v168 row_ror:8 row_mask:0xf bank_mask:0xf bound_ctrl:1
	v_fma_f32 v164, v94, v91, v169
	v_pk_fma_f32 v[148:149], v[74:75], v[166:167], v[148:149] op_sel_hi:[1,0,1]
	v_fma_f32 v171, v94, v93, v168
	v_fma_f32 v167, v166, v90, v164
	v_pk_fma_f32 v[150:151], v[76:77], v[166:167], v[150:151] op_sel_hi:[1,0,1]
	v_fma_f32 v171, v166, v92, v171
	v_cndmask_b32_e64 v162, v162, v168, s[44:45]
	v_pk_fma_f32 v[148:149], v[82:83], v[166:167], v[148:149] op_sel:[0,1,0] op_sel_hi:[1,1,1]
	v_pk_fma_f32 v[150:151], v[84:85], v[166:167], v[150:151] op_sel:[0,1,0] op_sel_hi:[1,1,1]
	v_cndmask_b32_e64 v162, v162, v171, s[42:43]
	v_pk_fma_f32 v[144:145], v[144:145], v[70:71], v[148:149]
	v_pk_fma_f32 v[146:147], v[146:147], v[72:73], v[150:151]
	v_mov_b64_e32 v[50:51], v[66:67]
	v_mov_b64_e32 v[52:53], v[68:69]
	v_mov_b64_e32 v[140:141], v[144:145]
	v_mov_b64_e32 v[142:143], v[146:147]
	v_mov_b32_e32 v111, v162
	s_add_i32 s9, s9, 1
	s_cmp_eq_u32 s9, 64
	s_cbranch_scc1 .LBB0_1115
	s_branch .LBB0_1092
